# out-projection row-statistic exchange: dropped the L1 invalidate in front of the sc1 slot reads
# speedup vs baseline: 1.0003x; 1.0003x over previous
;     __device__ __forceinline__ void fused(f32x4 (&acc)[2][2][4][2], const Unit& u, int wr, int wc, int fr, int fq, PG8_LAS unsigned char* lds, int wid, int lane) const {
;     ...
;             __hip_atomic_store(xbuf + (size_t)(u.pm * BM + row) * 4 + u.pn, tot, __ATOMIC_RELAXED, __HIP_MEMORY_SCOPE_AGENT); }
;         asm volatile("s_waitcnt vmcnt(0)" ::: "memory");
;         if (lane == 0) __hip_atomic_fetch_add(cnt + 64 * u.pm, 1u, __ATOMIC_RELAXED, __HIP_MEMORY_SCOPE_AGENT);
;         if (wid == 0) {
;             unsigned sp = 0;
;             for (;;) { if ((unsigned)__builtin_amdgcn_readfirstlane(__hip_atomic_load(cnt + 64 * u.pm, __ATOMIC_RELAXED, __HIP_MEMORY_SCOPE_AGENT)) >= 32u) break;
;                 if (++sp > (1u << 20)) break; __builtin_amdgcn_s_sleep(2); }
;             __builtin_amdgcn_fence(__ATOMIC_ACQUIRE, "agent");
;         }
;         asm volatile("s_waitcnt vmcnt(0) lgkmcnt(0)" ::: "memory"); __builtin_amdgcn_s_barrier(); asm volatile("" ::: "memory");
;         if (lane < 32) { const float* slot = xbuf + (size_t)(u.pm * BM + row) * 4; float tot = 0.f;
; #pragma unroll
;             for (int t = 0; t < 4; ++t) tot += __hip_atomic_load(slot + t, __ATOMIC_RELAXED, __HIP_MEMORY_SCOPE_AGENT);
;             Sr[row] = rsqrtf(tot * (1.0f / 1024.0f) + eps); }
.LBB0_1117:
	global_load_dword v152, v149, s[4:5] sc1
	v_subrev_co_u32_e32 v151, vcc, 1, v151
	s_waitcnt vmcnt(0)
	v_readfirstlane_b32 s6, v152
	s_cmp_gt_u32 s6, 31
	s_cselect_b64 s[6:7], -1, 0
	s_or_b64 s[6:7], s[6:7], vcc
	s_and_b64 vcc, exec, s[6:7]
	s_cbranch_vccz .LBB0_1116
.LBB0_1119:
	s_nop 0
.LBB0_1120:
	s_waitcnt vmcnt(0) lgkmcnt(0)
	s_barrier
	s_and_saveexec_b64 s[4:5], s[0:1]
	s_cbranch_execz .LBB0_1122
	v_lshl_add_u64 v[146:147], v[146:147], 4, s[2:3]
	global_load_dword v149, v[146:147], off sc1
	global_load_dword v151, v[146:147], off offset:4 sc1
	global_load_dword v152, v[146:147], off offset:8 sc1
	s_nop 0
	global_load_dword v146, v[146:147], off offset:12 sc1
	v_mov_b32_e32 v147, 0x358637bd
	s_mov_b32 s0, 0x800000
	s_waitcnt vmcnt(3)
	v_add_f32_e32 v149, 0, v149
	s_waitcnt vmcnt(2)
	v_add_f32_e32 v149, v149, v151
	s_waitcnt vmcnt(1)
	v_add_f32_e32 v149, v149, v152
	s_waitcnt vmcnt(0)
	v_add_f32_e32 v146, v149, v146
	v_fmac_f32_e32 v147, 0x3a800000, v146
	v_mul_f32_e32 v146, 0x4b800000, v147
	v_cmp_gt_f32_e32 vcc, s0, v147
	s_nop 1
	v_cndmask_b32_e32 v146, v147, v146, vcc
	v_rsq_f32_e32 v146, v146
	s_nop 0
	v_mul_f32_e32 v147, 0x45800000, v146
	v_cndmask_b32_e32 v146, v146, v147, vcc
	v_lshl_add_u32 v147, v150, 2, 0
	ds_write_b32 v147, v146 offset:4096
